# P4 row loop: second head group's lse loads issued with the first batch (one load round trip per row instead of two); includes mixa counted waits + QK read-ahead
# baseline (speedup 1.0000x reference)
; #define GAS __attribute__((address_space(1)))
; __device__ __forceinline__ void unpack8(v4u w, float (&f)[8]) { f[0] = bflo(w.x); f[1] = bfhi(w.x); f[2] = bflo(w.y); f[3] = bfhi(w.y); f[4] = bflo(w.z); f[5] = bfhi(w.z); f[6] = bflo(w.w); f[7] = bfhi(w.w); }
; __device__ __forceinline__ void mix_row(const bf16* __restrict__ OA, const float* __restrict__ LSE, const bf16* __restrict__ OC, bf16* __restrict__ mrow,
;                                         const float* __restrict__ ga, const float* __restrict__ gc, int m, int lane) {
;     v4u ra[2][3], rc[4];
; #pragma unroll
;     for (int j = 0; j < 2; ++j) { const int c = 8 * lane + 512 * j;
; #pragma unroll
;         for (int b = 0; b < 3; ++b) ra[j][b] = *(const GAS v4u*)(OA + ((size_t)b * M + m) * 1024 + c); }
; #pragma unroll
;     for (int j = 0; j < 4; ++j) rc[j] = *(const GAS v4u*)(OC + (size_t)m * 2048 + 8 * lane + 512 * j);
;     { float oa[2][8]; float s = 0.f;
; #pragma unroll
;       for (int j = 0; j < 2; ++j) { const int head = (lane >> 4) + 4 * j;
;         const float l0 = LSE[(size_t)m * 8 + head], l1 = LSE[((size_t)M + m) * 8 + head], l2 = LSE[((size_t)2 * M + m) * 8 + head];
;         const float mx = fmaxf(l0, fmaxf(l1, l2)); const float e0 = __expf(l0 - mx), e1 = __expf(l1 - mx), e2 = __expf(l2 - mx); const float inv = 1.0f / (e0 + e1 + e2);
;         float a0[8], a1[8], a2[8]; unpack8(ra[j][0], a0); unpack8(ra[j][1], a1); unpack8(ra[j][2], a2);
; #pragma unroll
;         for (int e = 0; e < 8; ++e) { oa[j][e] = a0[e] * (e0 * inv) + a1[e] * (e1 * inv) + a2[e] * (e2 * inv); s += oa[j][e] * oa[j][e]; } }
.LBB0_496:
	s_waitcnt lgkmcnt(0)
	v_lshl_add_u64 v[48:49], s[38:39], 0, v[74:75]
	v_add_co_u32_e32 v50, vcc, 0x60200000, v48
	s_mov_b32 s2, 0x6c380000
	s_nop 0
	v_addc_co_u32_e32 v51, vcc, 0, v49, vcc
	v_add_co_u32_e32 v52, vcc, 0x62200000, v48
	global_load_dwordx4 v[82:85], v[50:51], off
	s_nop 0
	v_addc_co_u32_e32 v53, vcc, 0, v49, vcc
	v_add_co_u32_e32 v48, vcc, 0x64200000, v48
	global_load_dwordx4 v[86:89], v[52:53], off
	s_nop 0
	v_addc_co_u32_e32 v49, vcc, 0, v49, vcc
	global_load_dwordx4 v[68:71], v[48:49], off
	global_load_dwordx4 v[98:101], v[50:51], off offset:1024
	global_load_dwordx4 v[102:105], v[52:53], off offset:1024
	global_load_dwordx4 v[64:67], v[48:49], off offset:1024
	v_lshl_add_u64 v[48:49], s[38:39], 0, v[76:77]
	v_add_co_u32_e32 v48, vcc, s2, v48
	v_lshl_add_u64 v[90:91], s[38:39], 0, v[72:73]
	s_nop 0
	v_addc_co_u32_e32 v49, vcc, 0, v49, vcc
	s_mov_b32 s2, 0x6c200000
	v_add_co_u32_e32 v92, vcc, s2, v90
	s_mov_b32 s2, 0x6c280000
	s_nop 0
	v_addc_co_u32_e32 v93, vcc, 0, v91, vcc
	v_add_co_u32_e32 v94, vcc, s2, v90
	s_mov_b32 s2, 0x6c300000
	s_nop 0
	v_addc_co_u32_e32 v95, vcc, 0, v91, vcc
	v_add_co_u32_e32 v90, vcc, s2, v90
	global_load_dwordx4 v[60:63], v[48:49], off
	global_load_dwordx4 v[56:59], v[48:49], off offset:1024
	global_load_dwordx4 v[52:55], v[48:49], off offset:2048
	s_nop 0
	global_load_dwordx4 v[48:51], v[48:49], off offset:3072
	v_addc_co_u32_e32 v91, vcc, 0, v91, vcc
	global_load_dword v96, v[92:93], off
	global_load_dword v97, v[94:95], off
	global_load_dword v108, v[90:91], off
	global_load_dword v140, v[92:93], off offset:16
	global_load_dword v141, v[94:95], off offset:16
	global_load_dword v142, v[90:91], off offset:16
	s_add_i32 s6, s6, s72
	v_lshl_add_u64 v[74:75], v[74:75], 0, s[74:75]
	v_lshl_add_u64 v[76:77], v[76:77], 0, s[36:37]
	v_lshl_add_u64 v[72:73], v[72:73], 0, s[60:61]
	s_cmpk_gt_i32 s6, 0x3fff
	s_waitcnt vmcnt(15)
	v_lshlrev_b32_e32 v121, 16, v83
	v_and_b32_e32 v123, 0xffff0000, v83
	v_lshlrev_b32_e32 v124, 16, v84
	v_and_b32_e32 v126, 0xffff0000, v84
	v_lshlrev_b32_e32 v129, 16, v85
	v_and_b32_e32 v131, 0xffff0000, v85
	s_waitcnt vmcnt(14)
	v_lshlrev_b32_e32 v120, 16, v86
	v_and_b32_e32 v122, 0xffff0000, v86
	v_and_b32_e32 v119, 0xffff0000, v87
	v_lshlrev_b32_e32 v125, 16, v89
	v_and_b32_e32 v127, 0xffff0000, v89
	v_lshlrev_b32_e32 v128, 16, v88
	v_and_b32_e32 v130, 0xffff0000, v88
	s_waitcnt vmcnt(10)
	v_and_b32_e32 v133, 0xffff0000, v67
	v_lshlrev_b32_e32 v132, 16, v67
	s_waitcnt vmcnt(3)
	v_max3_f32 v109, v96, v97, v108
	v_sub_f32_e32 v96, v96, v109
	v_mul_f32_e32 v96, 0x3fb8aa3b, v96
	v_exp_f32_e32 v107, v96
	v_sub_f32_e32 v96, v97, v109
	v_mul_f32_e32 v96, 0x3fb8aa3b, v96
	v_exp_f32_e32 v106, v96
	v_sub_f32_e32 v96, v108, v109
	v_mul_f32_e32 v96, 0x3fb8aa3b, v96
	v_exp_f32_e32 v96, v96
	v_add_f32_e32 v97, v107, v106
	v_add_f32_e32 v97, v96, v97
	v_div_scale_f32 v108, s[2:3], v97, v97, 1.0
	v_rcp_f32_e32 v109, v108
	s_nop 0
	v_fma_f32 v110, -v108, v109, 1.0
	v_fmac_f32_e32 v109, v110, v109
	v_div_scale_f32 v110, vcc, 1.0, v97, 1.0
	v_mul_f32_e32 v111, v110, v109
	v_fma_f32 v118, -v108, v111, v110
	v_fmac_f32_e32 v111, v118, v109
	v_fma_f32 v108, -v108, v111, v110
	v_lshlrev_b32_e32 v110, 16, v82
	v_and_b32_e32 v118, 0xffff0000, v82
	v_div_fmas_f32 v108, v108, v109, v111
	v_lshlrev_b32_e32 v111, 16, v87
	v_div_fixup_f32 v108, v108, v97, 1.0
	v_mul_f32_e32 v88, v96, v108
	v_lshlrev_b32_e32 v96, 16, v102
	v_and_b32_e32 v92, 0xffff0000, v102
	v_lshlrev_b32_e32 v95, 16, v103
	v_lshlrev_b32_e32 v94, 16, v98
	v_lshlrev_b32_e32 v97, 16, v99
	v_and_b32_e32 v93, 0xffff0000, v99
	v_and_b32_e32 v109, 0xffff0000, v104
	v_pk_mul_f32 v[134:135], v[106:107], v[108:109] op_sel_hi:[1,0]
	v_lshlrev_b32_e32 v108, 16, v70
	s_waitcnt vmcnt(0)
	v_mov_b32_e32 v82, v140
	v_mov_b32_e32 v83, v141
	v_mov_b32_e32 v84, v142
	v_max3_f32 v85, v82, v83, v84
	v_sub_f32_e32 v82, v82, v85
	v_sub_f32_e32 v83, v83, v85
	v_mul_f32_e32 v82, 0x3fb8aa3b, v82
	v_mul_f32_e32 v83, 0x3fb8aa3b, v83
	v_sub_f32_e32 v84, v84, v85
	v_exp_f32_e32 v82, v82
	v_exp_f32_e32 v83, v83
	v_mul_f32_e32 v84, 0x3fb8aa3b, v84
	v_exp_f32_e32 v85, v84
	v_add_f32_e32 v84, v82, v83
	v_add_f32_e32 v84, v85, v84
	v_div_scale_f32 v86, s[2:3], v84, v84, 1.0
	v_rcp_f32_e32 v87, v86
	s_nop 0
	v_fma_f32 v89, -v86, v87, 1.0
	v_fmac_f32_e32 v87, v89, v87
	v_div_scale_f32 v89, vcc, 1.0, v84, 1.0
	v_mul_f32_e32 v90, v89, v87
	v_fma_f32 v91, -v86, v90, v89
	v_fmac_f32_e32 v90, v91, v87
	v_fma_f32 v86, -v86, v90, v89
	v_div_fmas_f32 v86, v86, v87, v90
	v_div_fixup_f32 v84, v86, v84, 1.0
	v_and_b32_e32 v91, 0xffff0000, v103
	v_pk_mul_f32 v[102:103], v[82:83], v[84:85] op_sel_hi:[1,0]
	v_and_b32_e32 v90, 0xffff0000, v98
	v_pk_mov_b32 v[82:83], v[102:103], v[102:103] op_sel:[1,0]
	v_mul_f32_e32 v98, v85, v84
	v_and_b32_e32 v87, 0xffff0000, v101
	v_lshlrev_b32_e32 v86, 16, v105
	v_lshlrev_b32_e32 v85, 16, v100
	v_lshlrev_b32_e32 v84, 16, v66
	v_mov_b32_e32 v99, v83
	v_lshlrev_b32_e32 v89, 16, v104
	v_and_b32_e32 v105, 0xffff0000, v105
	v_lshlrev_b32_e32 v104, 16, v101
	v_pk_mul_f32 v[82:83], v[98:99], v[84:85]
	v_pk_mul_f32 v[84:85], v[102:103], v[86:87] op_sel:[1,0] op_sel_hi:[0,1]
	v_pk_fma_f32 v[84:85], v[102:103], v[104:105], v[84:85]
	v_lshlrev_b32_e32 v87, 16, v69
	v_pk_fma_f32 v[84:85], v[98:99], v[132:133], v[84:85] op_sel_hi:[0,1,1]
	v_lshlrev_b32_e32 v86, 16, v68
	v_and_b32_e32 v133, 0xffff0000, v69
	v_and_b32_e32 v132, 0xffff0000, v68
	v_pk_mul_f32 v[68:69], v[134:135], v[110:111] op_sel:[1,0] op_sel_hi:[0,1]
	v_pk_fma_f32 v[68:69], v[134:135], v[120:121], v[68:69]
	v_fma_f32 v67, v103, v89, v83
	v_pk_fma_f32 v[68:69], v[88:89], v[86:87], v[68:69] op_sel_hi:[0,1,1]
; #define GAS __attribute__((address_space(1)))
; __device__ __forceinline__ void unpack8(v4u w, float (&f)[8]) { f[0] = bflo(w.x); f[1] = bfhi(w.x); f[2] = bflo(w.y); f[3] = bfhi(w.y); f[4] = bflo(w.z); f[5] = bfhi(w.z); f[6] = bflo(w.w); f[7] = bfhi(w.w); }
; __device__ __forceinline__ v4u pack8(const float (&o)[8]) { v4u w; w.x = pk2(o[0], o[1]); w.y = pk2(o[2], o[3]); w.z = pk2(o[4], o[5]); w.w = pk2(o[6], o[7]); return w; }
; __device__ __forceinline__ void mix_row(const bf16* __restrict__ OA, const float* __restrict__ LSE, const bf16* __restrict__ OC, bf16* __restrict__ mrow,
;                                         const float* __restrict__ ga, const float* __restrict__ gc, int m, int lane) {
;     ...
;     { float oa[2][8]; float s = 0.f;
; #pragma unroll
;       for (int j = 0; j < 2; ++j) { const int head = (lane >> 4) + 4 * j;
;         const float l0 = LSE[(size_t)m * 8 + head], l1 = LSE[((size_t)M + m) * 8 + head], l2 = LSE[((size_t)2 * M + m) * 8 + head];
;         const float mx = fmaxf(l0, fmaxf(l1, l2)); const float e0 = __expf(l0 - mx), e1 = __expf(l1 - mx), e2 = __expf(l2 - mx); const float inv = 1.0f / (e0 + e1 + e2);
;         float a0[8], a1[8], a2[8]; unpack8(ra[j][0], a0); unpack8(ra[j][1], a1); unpack8(ra[j][2], a2);
; #pragma unroll
;         for (int e = 0; e < 8; ++e) { oa[j][e] = a0[e] * (e0 * inv) + a1[e] * (e1 * inv) + a2[e] * (e2 * inv); s += oa[j][e] * oa[j][e]; } }
;       const float rstd = 1.0f / sqrtf(wave_sum(s, lane) * (1.0f / 1024.0f) + EPS);
; #pragma unroll
;       for (int j = 0; j < 2; ++j) { const int c = 8 * lane + 512 * j; float o[8];
;         const f32x4 g0 = *(const GAS f32x4*)(ga + c), g1 = *(const GAS f32x4*)(ga + c + 4);
; #pragma unroll
;         for (int e = 0; e < 4; ++e) { o[e] = oa[j][e] * rstd * g0[e]; o[4 + e] = oa[j][4 + e] * rstd * g1[e]; }
;         *(GAS v4u*)(mrow + c) = pack8(o); } }
	v_pk_mul_f32 v[86:87], v[134:135], v[118:119] op_sel:[1,0] op_sel_hi:[0,1]
	v_add_f32_e32 v82, v82, v67
	v_and_b32_e32 v67, 0xffff0000, v100
	v_and_b32_e32 v66, 0xffff0000, v66
	v_pk_fma_f32 v[86:87], v[134:135], v[122:123], v[86:87]
	v_pk_mul_f32 v[66:67], v[98:99], v[66:67]
	v_pk_fma_f32 v[86:87], v[88:89], v[132:133], v[86:87] op_sel_hi:[0,1,1]
	v_fma_f32 v67, v103, v109, v67
	v_pk_mul_f32 v[104:105], v[68:69], v[68:69]
	v_pk_mul_f32 v[106:107], v[86:87], v[86:87]
	v_lshlrev_b32_e32 v109, 16, v71
	v_and_b32_e32 v111, 0xffff0000, v71
	v_and_b32_e32 v110, 0xffff0000, v70
	v_pk_mul_f32 v[70:71], v[134:135], v[124:125] op_sel:[1,0] op_sel_hi:[0,1]
	v_add_f32_e32 v66, v66, v67
	v_pk_fma_f32 v[70:71], v[134:135], v[128:129], v[70:71]
	v_pk_mul_f32 v[118:119], v[134:135], v[126:127] op_sel:[1,0] op_sel_hi:[0,1]
	v_add_f32_e32 v67, v104, v106
	v_pk_fma_f32 v[70:71], v[88:89], v[108:109], v[70:71] op_sel_hi:[0,1,1]
	v_pk_fma_f32 v[118:119], v[134:135], v[130:131], v[118:119]
	v_add_f32_e32 v67, v105, v67
	v_pk_mul_f32 v[108:109], v[70:71], v[70:71]
	v_pk_fma_f32 v[88:89], v[88:89], v[110:111], v[118:119] op_sel_hi:[0,1,1]
	v_add_f32_e32 v67, v107, v67
	v_pk_mul_f32 v[110:111], v[88:89], v[88:89]
	v_pk_mul_f32 v[94:95], v[102:103], v[94:95]
	v_add_f32_e32 v67, v108, v67
	v_lshlrev_b32_e32 v121, 16, v65
	v_lshlrev_b32_e32 v120, 16, v64
	v_pk_fma_f32 v[94:95], v[102:103], v[96:97], v[94:95] op_sel:[1,0,0] op_sel_hi:[0,1,1]
	v_pk_mul_f32 v[90:91], v[102:103], v[90:91]
	v_add_f32_e32 v67, v110, v67
	v_and_b32_e32 v65, 0xffff0000, v65
	v_and_b32_e32 v64, 0xffff0000, v64
	v_pk_fma_f32 v[94:95], v[98:99], v[120:121], v[94:95] op_sel_hi:[0,1,1]
	v_pk_fma_f32 v[90:91], v[102:103], v[92:93], v[90:91] op_sel:[1,0,0] op_sel_hi:[0,1,1]
	v_add_f32_e32 v67, v109, v67
	v_pk_mul_f32 v[96:97], v[94:95], v[94:95]
	v_pk_fma_f32 v[90:91], v[98:99], v[64:65], v[90:91] op_sel_hi:[0,1,1]
	v_add_f32_e32 v67, v111, v67
	v_pk_mul_f32 v[64:65], v[90:91], v[90:91]
	v_add_f32_e32 v67, v96, v67
	v_add_f32_e32 v64, v64, v67
	v_add_f32_e32 v64, v97, v64
	v_add_f32_e32 v64, v65, v64
	v_fmac_f32_e32 v64, v82, v82
	v_pk_mul_f32 v[100:101], v[84:85], v[84:85]
	v_fmac_f32_e32 v64, v66, v66
	v_add_f32_e32 v64, v100, v64
	v_add_f32_e32 v64, v101, v64
	ds_bpermute_b32 v65, v1, v64
	v_lshl_add_u64 v[118:119], s[38:39], 0, v[78:79]
	v_lshlrev_b32_e32 v101, 16, v59
	v_lshlrev_b32_e32 v100, 16, v58
	v_and_b32_e32 v59, 0xffff0000, v59
	s_waitcnt lgkmcnt(0)
	v_add_f32_e32 v64, v64, v65
	ds_bpermute_b32 v65, v112, v64
	v_and_b32_e32 v58, 0xffff0000, v58
	v_pk_mul_f32 v[102:103], v[100:101], v[100:101]
	v_pk_mul_f32 v[104:105], v[58:59], v[58:59]
	v_lshlrev_b32_e32 v107, 16, v53
	s_waitcnt lgkmcnt(0)
	v_add_f32_e32 v64, v64, v65
	ds_bpermute_b32 v65, v113, v64
	v_lshlrev_b32_e32 v106, 16, v52
	v_and_b32_e32 v53, 0xffff0000, v53
	v_and_b32_e32 v52, 0xffff0000, v52
	v_pk_mul_f32 v[108:109], v[106:107], v[106:107]
	s_waitcnt lgkmcnt(0)
	v_add_f32_e32 v64, v64, v65
	ds_bpermute_b32 v65, v115, v64
	v_pk_mul_f32 v[110:111], v[52:53], v[52:53]
	v_lshlrev_b32_e32 v125, 16, v49
	v_lshlrev_b32_e32 v124, 16, v48
	v_and_b32_e32 v127, 0xffff0000, v49
	s_waitcnt lgkmcnt(0)
	v_add_f32_e32 v64, v64, v65
	ds_bpermute_b32 v65, v116, v64
	v_and_b32_e32 v126, 0xffff0000, v48
	v_pk_mul_f32 v[48:49], v[124:125], v[124:125]
	v_pk_mul_f32 v[128:129], v[126:127], v[126:127]
	v_lshl_add_u64 v[78:79], v[78:79], 0, s[88:89]
	s_waitcnt lgkmcnt(0)
	v_add_f32_e32 v64, v64, v65
	ds_bpermute_b32 v65, v117, v64
	s_waitcnt lgkmcnt(0)
	v_add_f32_e32 v64, v64, v65
	v_fmamk_f32 v64, v64, 0x3a800000, v204
	v_cmp_gt_f32_e32 vcc, s73, v64
	v_mul_f32_e32 v65, 0x4f800000, v64
	s_nop 0
	v_cndmask_b32_e32 v64, v64, v65, vcc
	v_sqrt_f32_e32 v65, v64
	s_nop 0
	v_add_u32_e32 v67, -1, v65
	v_fma_f32 v83, -v67, v65, v64
	v_cmp_ge_f32_e64 s[40:41], 0, v83
	v_add_u32_e32 v83, 1, v65
	s_nop 0
	v_cndmask_b32_e64 v67, v65, v67, s[40:41]
	v_fma_f32 v65, -v83, v65, v64
	v_cmp_lt_f32_e64 s[40:41], 0, v65
	s_nop 1
	v_cndmask_b32_e64 v65, v67, v83, s[40:41]
	v_mul_f32_e32 v67, 0x37800000, v65
	v_cndmask_b32_e32 v65, v65, v67, vcc
	v_cmp_class_f32_e32 vcc, v64, v205
	s_nop 1
	v_cndmask_b32_e32 v64, v65, v64, vcc
	v_div_scale_f32 v65, s[2:3], v64, v64, 1.0
	v_rcp_f32_e32 v67, v65
	s_mov_b32 s2, 0x35201000
	v_fma_f32 v83, -v65, v67, 1.0
	v_fmac_f32_e32 v67, v83, v67
	v_div_scale_f32 v83, vcc, 1.0, v64, 1.0
	v_mul_f32_e32 v92, v83, v67
	v_fma_f32 v93, -v65, v92, v83
	v_fmac_f32_e32 v92, v93, v67
	v_fma_f32 v65, -v65, v92, v83
	v_div_fmas_f32 v65, v65, v67, v92
	v_div_fixup_f32 v92, v65, v64, 1.0
	v_pk_mul_f32 v[64:65], v[68:69], v[92:93] op_sel_hi:[1,0]
	v_pk_mul_f32 v[68:69], v[70:71], v[92:93] op_sel_hi:[1,0]
	v_pk_mul_f32 v[70:71], v[86:87], v[92:93] op_sel_hi:[1,0]
	v_pk_mul_f32 v[86:87], v[88:89], v[92:93] op_sel_hi:[1,0]
	v_pk_mul_f32 v[70:71], v[32:33], v[70:71]
	v_pk_mul_f32 v[86:87], v[36:37], v[86:87]
	v_pk_mul_f32 v[64:65], v[34:35], v[64:65]
	v_pk_mul_f32 v[68:69], v[38:39], v[68:69]
	v_bfe_u32 v83, v86, 16, 1
	v_bfe_u32 v88, v71, 16, 1
	v_bfe_u32 v89, v70, 16, 1
	v_bfe_u32 v67, v87, 16, 1
	v_add3_u32 v89, v70, v89, s14
	v_add3_u32 v88, v71, v88, s14
	v_add3_u32 v70, v86, v83, s14
	v_bfe_u32 v71, v64, 16, 1
	v_bfe_u32 v86, v68, 16, 1
	v_add3_u32 v67, v87, v67, s14
	v_bfe_u32 v83, v65, 16, 1
	v_bfe_u32 v87, v69, 16, 1
	v_add3_u32 v68, v68, v86, s14
	v_add3_u32 v64, v64, v71, s14
	v_add_co_u32_e32 v86, vcc, s63, v118
	v_add3_u32 v69, v69, v87, s14
	v_add3_u32 v65, v65, v83, s14
	v_lshrrev_b32_e32 v64, 16, v64
	v_lshrrev_b32_e32 v68, 16, v68
	v_addc_co_u32_e32 v87, vcc, 0, v119, vcc
	v_lshrrev_b32_e32 v65, 16, v65
	v_lshrrev_b32_e32 v69, 16, v69
; #define GAS __attribute__((address_space(1)))
; __device__ __forceinline__ void unpack8(v4u w, float (&f)[8]) { f[0] = bflo(w.x); f[1] = bfhi(w.x); f[2] = bflo(w.y); f[3] = bfhi(w.y); f[4] = bflo(w.z); f[5] = bfhi(w.z); f[6] = bflo(w.w); f[7] = bfhi(w.w); }
; __device__ __forceinline__ v4u pack8(const float (&o)[8]) { v4u w; w.x = pk2(o[0], o[1]); w.y = pk2(o[2], o[3]); w.z = pk2(o[4], o[5]); w.w = pk2(o[6], o[7]); return w; }
; __device__ __forceinline__ void mix_row(const bf16* __restrict__ OA, const float* __restrict__ LSE, const bf16* __restrict__ OC, bf16* __restrict__ mrow,
;                                         const float* __restrict__ ga, const float* __restrict__ gc, int m, int lane) {
;     ...
;       for (int j = 0; j < 2; ++j) { const int c = 8 * lane + 512 * j; float o[8];
;         const f32x4 g0 = *(const GAS f32x4*)(ga + c), g1 = *(const GAS f32x4*)(ga + c + 4);
; #pragma unroll
;         for (int e = 0; e < 4; ++e) { o[e] = oa[j][e] * rstd * g0[e]; o[4 + e] = oa[j][4 + e] * rstd * g1[e]; }
;         *(GAS v4u*)(mrow + c) = pack8(o); } }
;     { float oc[4][8]; float s = 0.f;
; #pragma unroll
;       for (int j = 0; j < 4; ++j) { unpack8(rc[j], oc[j]);
; #pragma unroll
;         for (int e = 0; e < 8; ++e) s += oc[j][e] * oc[j][e]; }
;       const float rstd = 1.0f / sqrtf(wave_sum(s, lane) * (1.0f / 2048.0f) + EPS);
	v_and_or_b32 v70, v70, s33, v68
	v_and_or_b32 v68, v89, s33, v64
	v_add_co_u32_e32 v64, vcc, s2, v118
	v_and_or_b32 v71, v67, s33, v69
	v_and_or_b32 v69, v88, s33, v65
	v_addc_co_u32_e32 v65, vcc, 0, v119, vcc
	v_mov_b32_e32 v67, v85
	global_store_dwordx4 v[64:65], v[68:71], off offset:-4096
	v_mov_b32_e32 v83, v84
	v_pk_mul_f32 v[66:67], v[66:67], v[92:93] op_sel_hi:[1,0]
	v_pk_mul_f32 v[70:71], v[90:91], v[92:93] op_sel_hi:[1,0]
	v_pk_mul_f32 v[68:69], v[94:95], v[92:93] op_sel_hi:[1,0]
	v_pk_mul_f32 v[70:71], v[40:41], v[70:71]
	v_pk_mul_f32 v[82:83], v[82:83], v[92:93] op_sel_hi:[1,0]
	v_pk_mul_f32 v[66:67], v[44:45], v[66:67]
	v_pk_mul_f32 v[68:69], v[42:43], v[68:69]
	v_pk_mul_f32 v[82:83], v[46:47], v[82:83]
	v_bfe_u32 v84, v67, 16, 1
	v_bfe_u32 v85, v66, 16, 1
	v_bfe_u32 v88, v71, 16, 1
	v_bfe_u32 v89, v70, 16, 1
	v_add3_u32 v70, v70, v89, s14
	v_add3_u32 v71, v71, v88, s14
	v_add3_u32 v66, v66, v85, s14
	v_add3_u32 v67, v67, v84, s14
	v_bfe_u32 v84, v68, 16, 1
	v_bfe_u32 v85, v69, 16, 1
	v_bfe_u32 v88, v82, 16, 1
	v_bfe_u32 v89, v83, 16, 1
	v_add3_u32 v83, v83, v89, s14
	v_add3_u32 v82, v82, v88, s14
	v_add3_u32 v69, v69, v85, s14
	v_add3_u32 v68, v68, v84, s14
	v_lshrrev_b32_e32 v84, 16, v68
	v_lshrrev_b32_e32 v85, 16, v69
	v_lshrrev_b32_e32 v68, 16, v82
	v_lshrrev_b32_e32 v69, 16, v83
	v_and_or_b32 v69, v67, s33, v69
	v_and_or_b32 v68, v66, s33, v68
	v_and_or_b32 v67, v71, s33, v85
	v_and_or_b32 v66, v70, s33, v84
	v_lshlrev_b32_e32 v83, 16, v61
	v_lshlrev_b32_e32 v82, 16, v60
	v_and_b32_e32 v61, 0xffff0000, v61
	v_and_b32_e32 v60, 0xffff0000, v60
	global_store_dwordx4 v[86:87], v[66:69], off offset:1024
	v_pk_mul_f32 v[84:85], v[82:83], v[82:83]
	v_pk_mul_f32 v[86:87], v[60:61], v[60:61]
	v_lshlrev_b32_e32 v89, 16, v63
	v_add_f32_e32 v67, v84, v86
	v_lshlrev_b32_e32 v88, 16, v62
	v_add_f32_e32 v67, v85, v67
	v_and_b32_e32 v63, 0xffff0000, v63
	v_and_b32_e32 v62, 0xffff0000, v62
	v_pk_mul_f32 v[90:91], v[88:89], v[88:89]
	v_add_f32_e32 v67, v87, v67
	v_pk_mul_f32 v[92:93], v[62:63], v[62:63]
	v_add_f32_e32 v67, v90, v67
	v_add_f32_e32 v67, v92, v67
	v_lshlrev_b32_e32 v95, 16, v57
	v_lshlrev_b32_e32 v94, 16, v56
	v_add_f32_e32 v67, v91, v67
	v_and_b32_e32 v57, 0xffff0000, v57
	v_and_b32_e32 v56, 0xffff0000, v56
	v_pk_mul_f32 v[96:97], v[94:95], v[94:95]
	v_add_f32_e32 v67, v93, v67
	v_pk_mul_f32 v[98:99], v[56:57], v[56:57]
	v_add_f32_e32 v67, v96, v67
	v_add_f32_e32 v67, v98, v67
	v_add_f32_e32 v67, v97, v67
	v_add_f32_e32 v67, v99, v67
	v_add_f32_e32 v67, v102, v67
	v_add_f32_e32 v67, v104, v67
	v_add_f32_e32 v67, v103, v67
	v_add_f32_e32 v67, v105, v67
	v_add_f32_e32 v67, v108, v67
	v_add_f32_e32 v67, v110, v67
	v_lshlrev_b32_e32 v119, 16, v55
	v_lshlrev_b32_e32 v118, 16, v54
	v_add_f32_e32 v67, v109, v67
	v_and_b32_e32 v55, 0xffff0000, v55
	v_and_b32_e32 v54, 0xffff0000, v54
	v_pk_mul_f32 v[120:121], v[118:119], v[118:119]
	v_add_f32_e32 v67, v111, v67
	v_pk_mul_f32 v[122:123], v[54:55], v[54:55]
	v_add_f32_e32 v67, v120, v67
	v_add_f32_e32 v67, v122, v67
	v_add_f32_e32 v67, v121, v67
	v_add_f32_e32 v67, v123, v67
	v_add_f32_e32 v48, v48, v67
	v_add_f32_e32 v48, v128, v48
	v_add_f32_e32 v48, v49, v48
	v_lshlrev_b32_e32 v66, 16, v50
	v_add_f32_e32 v48, v129, v48
	v_and_b32_e32 v68, 0xffff0000, v50
	v_and_b32_e32 v70, 0xffff0000, v51
	v_lshlrev_b32_e32 v71, 16, v51
	v_fmac_f32_e32 v48, v66, v66
	v_pk_mul_f32 v[50:51], v[70:71], v[70:71]
	v_fmac_f32_e32 v48, v68, v68
	v_add_f32_e32 v48, v51, v48
	v_add_f32_e32 v48, v50, v48
	ds_bpermute_b32 v49, v1, v48
	s_waitcnt lgkmcnt(0)
	v_add_f32_e32 v48, v48, v49
	ds_bpermute_b32 v49, v112, v48
	s_waitcnt lgkmcnt(0)
	v_add_f32_e32 v48, v48, v49
	ds_bpermute_b32 v49, v113, v48
	s_waitcnt lgkmcnt(0)
	v_add_f32_e32 v48, v48, v49
	ds_bpermute_b32 v49, v115, v48
	s_waitcnt lgkmcnt(0)
	v_add_f32_e32 v48, v48, v49
	ds_bpermute_b32 v49, v116, v48
	s_waitcnt lgkmcnt(0)
	v_add_f32_e32 v48, v48, v49
	ds_bpermute_b32 v49, v117, v48
	s_waitcnt lgkmcnt(0)
; #define GAS __attribute__((address_space(1)))
; __device__ __forceinline__ v4u pack8(const float (&o)[8]) { v4u w; w.x = pk2(o[0], o[1]); w.y = pk2(o[2], o[3]); w.z = pk2(o[4], o[5]); w.w = pk2(o[6], o[7]); return w; }
; __device__ __forceinline__ void mix_row(const bf16* __restrict__ OA, const float* __restrict__ LSE, const bf16* __restrict__ OC, bf16* __restrict__ mrow,
;                                         const float* __restrict__ ga, const float* __restrict__ gc, int m, int lane) {
;     ...
;       const float rstd = 1.0f / sqrtf(wave_sum(s, lane) * (1.0f / 2048.0f) + EPS);
; #pragma unroll
;       for (int j = 0; j < 4; ++j) { const int c = 8 * lane + 512 * j; float o[8];
;         const f32x4 g0 = *(const GAS f32x4*)(gc + c), g1 = *(const GAS f32x4*)(gc + c + 4);
; #pragma unroll
;         for (int e = 0; e < 4; ++e) { o[e] = oc[j][e] * rstd * g0[e]; o[4 + e] = oc[j][4 + e] * rstd * g1[e]; }
;         *(GAS v4u*)(mrow + 2048 + c) = pack8(o); } }
	v_add_f32_e32 v48, v48, v49
	v_fmamk_f32 v48, v48, 0x3a000000, v204
	v_cmp_gt_f32_e32 vcc, s73, v48
	v_mul_f32_e32 v49, 0x4f800000, v48
	s_nop 0
	v_cndmask_b32_e32 v48, v48, v49, vcc
	v_sqrt_f32_e32 v49, v48
	s_nop 0
	v_add_u32_e32 v50, -1, v49
	v_fma_f32 v51, -v50, v49, v48
	v_cmp_ge_f32_e64 s[40:41], 0, v51
	v_add_u32_e32 v51, 1, v49
	s_nop 0
	v_cndmask_b32_e64 v50, v49, v50, s[40:41]
	v_fma_f32 v49, -v51, v49, v48
	v_cmp_lt_f32_e64 s[40:41], 0, v49
	s_nop 1
	v_cndmask_b32_e64 v49, v50, v51, s[40:41]
	v_mul_f32_e32 v50, 0x37800000, v49
	v_cndmask_b32_e32 v49, v49, v50, vcc
	v_cmp_class_f32_e32 vcc, v48, v205
	s_nop 1
	v_cndmask_b32_e32 v48, v49, v48, vcc
	v_div_scale_f32 v49, s[2:3], v48, v48, 1.0
	v_rcp_f32_e32 v50, v49
	s_nop 0
	v_fma_f32 v51, -v49, v50, 1.0
	v_fmac_f32_e32 v50, v51, v50
	v_div_scale_f32 v51, vcc, 1.0, v48, 1.0
	v_mul_f32_e32 v67, v51, v50
	v_fma_f32 v69, -v49, v67, v51
	v_fmac_f32_e32 v67, v69, v50
	v_fma_f32 v49, -v49, v67, v51
	v_div_fmas_f32 v49, v49, v50, v67
	v_div_fixup_f32 v84, v49, v48, 1.0
	v_pk_mul_f32 v[60:61], v[84:85], v[60:61] op_sel_hi:[0,1]
	v_pk_mul_f32 v[62:63], v[84:85], v[62:63] op_sel_hi:[0,1]
	v_pk_mul_f32 v[48:49], v[84:85], v[82:83] op_sel_hi:[0,1]
	v_pk_mul_f32 v[50:51], v[84:85], v[88:89] op_sel_hi:[0,1]
	v_pk_mul_f32 v[60:61], v[80:81], v[60:61]
	v_pk_mul_f32 v[62:63], v[4:5], v[62:63]
	v_pk_mul_f32 v[48:49], v[2:3], v[48:49]
	v_pk_mul_f32 v[50:51], v[6:7], v[50:51]
	v_bfe_u32 v67, v63, 16, 1
	v_bfe_u32 v69, v62, 16, 1
	v_bfe_u32 v82, v61, 16, 1
	v_bfe_u32 v83, v60, 16, 1
	v_add3_u32 v60, v60, v83, s14
	v_add3_u32 v61, v61, v82, s14
	v_add3_u32 v62, v62, v69, s14
	v_add3_u32 v63, v63, v67, s14
	v_bfe_u32 v67, v48, 16, 1
	v_bfe_u32 v69, v49, 16, 1
	v_bfe_u32 v82, v50, 16, 1
	v_bfe_u32 v83, v51, 16, 1
	v_add3_u32 v51, v51, v83, s14
	v_add3_u32 v50, v50, v82, s14
	v_add3_u32 v49, v49, v69, s14
	v_add3_u32 v48, v48, v67, s14
	v_lshrrev_b32_e32 v48, 16, v48
	v_lshrrev_b32_e32 v49, 16, v49
	v_lshrrev_b32_e32 v50, 16, v50
	v_lshrrev_b32_e32 v51, 16, v51
	v_and_or_b32 v51, v63, s33, v51
	v_and_or_b32 v50, v62, s33, v50
	v_and_or_b32 v49, v61, s33, v49
	v_and_or_b32 v48, v60, s33, v48
	v_pk_mul_f32 v[56:57], v[84:85], v[56:57] op_sel_hi:[0,1]
	v_pk_mul_f32 v[58:59], v[84:85], v[58:59] op_sel_hi:[0,1]
	global_store_dwordx4 v[64:65], v[48:51], off
	v_pk_mul_f32 v[56:57], v[8:9], v[56:57]
	v_pk_mul_f32 v[58:59], v[12:13], v[58:59]
	v_pk_mul_f32 v[48:49], v[84:85], v[94:95] op_sel_hi:[0,1]
	v_pk_mul_f32 v[50:51], v[84:85], v[100:101] op_sel_hi:[0,1]
	v_pk_mul_f32 v[48:49], v[10:11], v[48:49]
	v_pk_mul_f32 v[50:51], v[14:15], v[50:51]
	v_bfe_u32 v60, v59, 16, 1
	v_bfe_u32 v61, v58, 16, 1
	v_bfe_u32 v62, v57, 16, 1
	v_bfe_u32 v63, v56, 16, 1
	v_add3_u32 v56, v56, v63, s14
	v_add3_u32 v57, v57, v62, s14
	v_add3_u32 v58, v58, v61, s14
	v_add3_u32 v59, v59, v60, s14
	v_bfe_u32 v60, v48, 16, 1
	v_bfe_u32 v61, v49, 16, 1
	v_bfe_u32 v62, v50, 16, 1
	v_bfe_u32 v63, v51, 16, 1
	v_add3_u32 v51, v51, v63, s14
	v_add3_u32 v50, v50, v62, s14
	v_add3_u32 v49, v49, v61, s14
	v_add3_u32 v48, v48, v60, s14
	v_lshrrev_b32_e32 v48, 16, v48
	v_lshrrev_b32_e32 v49, 16, v49
	v_lshrrev_b32_e32 v50, 16, v50
	v_lshrrev_b32_e32 v51, 16, v51
	v_and_or_b32 v51, v59, s33, v51
	v_and_or_b32 v50, v58, s33, v50
	v_and_or_b32 v49, v57, s33, v49
	v_and_or_b32 v48, v56, s33, v48
	v_pk_mul_f32 v[52:53], v[84:85], v[52:53] op_sel_hi:[0,1]
	v_pk_mul_f32 v[54:55], v[84:85], v[54:55] op_sel_hi:[0,1]
	global_store_dwordx4 v[64:65], v[48:51], off offset:1024
	v_pk_mul_f32 v[52:53], v[16:17], v[52:53]
	v_pk_mul_f32 v[54:55], v[20:21], v[54:55]
	v_pk_mul_f32 v[48:49], v[84:85], v[106:107] op_sel_hi:[0,1]
	v_pk_mul_f32 v[50:51], v[84:85], v[118:119] op_sel_hi:[0,1]
	v_pk_mul_f32 v[48:49], v[18:19], v[48:49]
	v_pk_mul_f32 v[50:51], v[22:23], v[50:51]
	v_bfe_u32 v56, v55, 16, 1
	v_bfe_u32 v57, v54, 16, 1
	v_bfe_u32 v58, v53, 16, 1
	v_bfe_u32 v59, v52, 16, 1
	v_add3_u32 v52, v52, v59, s14
	v_add3_u32 v53, v53, v58, s14
	v_add3_u32 v54, v54, v57, s14
	v_add3_u32 v55, v55, v56, s14
	v_bfe_u32 v56, v48, 16, 1
	v_bfe_u32 v57, v49, 16, 1
	v_bfe_u32 v58, v50, 16, 1
	v_bfe_u32 v59, v51, 16, 1
	v_add3_u32 v51, v51, v59, s14
	v_add3_u32 v50, v50, v58, s14
	v_add3_u32 v49, v49, v57, s14
	v_add3_u32 v48, v48, v56, s14
	v_lshrrev_b32_e32 v48, 16, v48
	v_lshrrev_b32_e32 v49, 16, v49
	v_lshrrev_b32_e32 v50, 16, v50
	v_lshrrev_b32_e32 v51, 16, v51
	v_and_or_b32 v51, v55, s33, v51
	v_and_or_b32 v50, v54, s33, v50
	v_and_or_b32 v49, v53, s33, v49
	v_and_or_b32 v48, v52, s33, v48
	v_mov_b32_e32 v69, v70
	global_store_dwordx4 v[64:65], v[48:51], off offset:2048
	v_mov_b32_e32 v67, v71
	v_pk_mul_f32 v[54:55], v[84:85], v[68:69] op_sel_hi:[0,1]
	v_pk_mul_f32 v[50:51], v[84:85], v[126:127] op_sel_hi:[0,1]
	v_pk_mul_f32 v[48:49], v[84:85], v[124:125] op_sel_hi:[0,1]
	v_pk_mul_f32 v[50:51], v[24:25], v[50:51]
	v_pk_mul_f32 v[52:53], v[84:85], v[66:67] op_sel_hi:[0,1]
	v_pk_mul_f32 v[54:55], v[28:29], v[54:55]
	v_pk_mul_f32 v[48:49], v[26:27], v[48:49]
	v_pk_mul_f32 v[52:53], v[30:31], v[52:53]
	v_bfe_u32 v56, v55, 16, 1
	v_bfe_u32 v57, v54, 16, 1
	v_bfe_u32 v58, v51, 16, 1
	v_bfe_u32 v59, v50, 16, 1
	v_add3_u32 v59, v50, v59, s14
	v_add3_u32 v58, v51, v58, s14
	v_add3_u32 v50, v54, v57, s14
	v_add3_u32 v51, v55, v56, s14
	v_bfe_u32 v54, v48, 16, 1
	v_bfe_u32 v55, v49, 16, 1
	v_bfe_u32 v56, v52, 16, 1
	v_bfe_u32 v57, v53, 16, 1
	v_add3_u32 v53, v53, v57, s14
	v_add3_u32 v52, v52, v56, s14
	v_add3_u32 v49, v49, v55, s14
	v_add3_u32 v48, v48, v54, s14
	v_lshrrev_b32_e32 v48, 16, v48
	v_lshrrev_b32_e32 v49, 16, v49
	v_lshrrev_b32_e32 v52, 16, v52
	v_lshrrev_b32_e32 v53, 16, v53
	v_and_or_b32 v51, v51, s33, v53
	v_and_or_b32 v50, v50, s33, v52
	v_and_or_b32 v49, v58, s33, v49
	v_and_or_b32 v48, v59, s33, v48
	global_store_dwordx4 v[64:65], v[48:51], off offset:3072
	s_cbranch_scc0 .LBB0_496
